# head-epilogue rope: cos/sin loads of block pairs 2-4 issued ahead of the previous block's output stores; first-block waits leave those 2 stores outstanding
# speedup vs baseline: 1.0065x; 1.0003x over previous
.LBB0_274:
	s_and_b64 vcc, exec, s[42:43]
	s_cbranch_vccnz .Lrope_pf1
	v_add_u32_e32 v96, 32, v190
	v_ashrrev_i32_e32 v97, 31, v96
	v_readlane_b32 s2, v251, 12
	v_lshlrev_b64 v[96:97], 6, v[96:97]
	v_readlane_b32 s3, v251, 13
	s_nop 1
	v_lshl_add_u64 v[96:97], s[2:3], 0, v[96:97]
	global_load_dwordx4 v[154:157], v[96:97], off offset:48
	global_load_dwordx4 v[162:165], v[96:97], off offset:32
	global_load_dwordx4 v[158:161], v[96:97], off offset:16
	global_load_dwordx4 v[166:169], v[96:97], off
	v_add_u32_e32 v96, 48, v190
	v_ashrrev_i32_e32 v97, 31, v96
	v_lshlrev_b64 v[96:97], 6, v[96:97]
	v_lshl_add_u64 v[96:97], s[2:3], 0, v[96:97]
	global_load_dwordx4 v[138:141], v[96:97], off offset:48
	global_load_dwordx4 v[146:149], v[96:97], off offset:32
	global_load_dwordx4 v[142:145], v[96:97], off offset:16
	global_load_dwordx4 v[150:153], v[96:97], off
.Lrope_pf1:
	v_add_u32_e32 v96, 16, v220
	v_mad_i64_i32 v[96:97], s[2:3], s10, v96, 0
	v_pk_mul_f32 v[100:101], v[132:133], v[104:105]
	v_pk_mul_f32 v[104:105], v[182:183], v[106:107]
	v_pk_mul_f32 v[106:107], v[128:129], v[108:109]
	v_lshl_add_u64 v[108:109], v[96:97], 1, v[184:185]
	v_cvt_pk_bf16_f32 v96, v112, v113
	v_cvt_pk_bf16_f32 v97, v110, v111
	v_cvt_pk_bf16_f32 v98, v116, v117
	v_cvt_pk_bf16_f32 v99, v114, v115
	v_pk_mul_f32 v[102:103], v[130:131], v[102:103]
	global_store_dwordx4 v[108:109], v[96:99], off
	s_and_b64 vcc, exec, s[42:43]
	s_nop 0
	v_cvt_pk_bf16_f32 v96, v102, v103
	v_cvt_pk_bf16_f32 v97, v100, v101
	v_cvt_pk_bf16_f32 v98, v106, v107
	v_cvt_pk_bf16_f32 v99, v104, v105
	global_store_dwordx4 v[108:109], v[96:99], off offset:64
	s_cbranch_vccnz .LBB0_276
.LBB0_276:
	s_nop 0
	v_add_f32_e32 v96, v242, v243
	v_fmamk_f32 v96, v96, 0x3a800000, v231
	v_rsq_f32_e32 v102, v96
	s_and_b64 vcc, exec, s[40:41]
	v_pk_mul_f32 v[94:95], v[94:95], v[102:103] op_sel_hi:[1,0]
	v_pk_mul_f32 v[96:97], v[92:93], v[102:103] op_sel_hi:[1,0]
	v_pk_mul_f32 v[98:99], v[90:91], v[102:103] op_sel_hi:[1,0]
	v_pk_mul_f32 v[100:101], v[88:89], v[102:103] op_sel_hi:[1,0]
	v_pk_mul_f32 v[88:89], v[86:87], v[102:103] op_sel_hi:[1,0]
	v_pk_mul_f32 v[86:87], v[84:85], v[102:103] op_sel_hi:[1,0]
	v_pk_mul_f32 v[90:91], v[82:83], v[102:103] op_sel_hi:[1,0]
	v_pk_mul_f32 v[92:93], v[80:81], v[102:103] op_sel_hi:[1,0]
	s_cbranch_vccnz .LBB0_278
	v_mul_f32_e32 v80, v97, v97
	v_mul_f32_e32 v81, v95, v95
	v_fmac_f32_e32 v80, v96, v96
	v_fmac_f32_e32 v81, v94, v94
	v_add_f32_e32 v80, v80, v81
	v_mul_f32_e32 v81, v101, v101
	v_mul_f32_e32 v82, v99, v99
	v_fmac_f32_e32 v81, v100, v100
	v_fmac_f32_e32 v82, v98, v98
	v_add_f32_e32 v81, v81, v82
	v_add_f32_e32 v80, v80, v81
	v_mul_f32_e32 v81, v87, v87
	v_mul_f32_e32 v82, v89, v89
	v_fmac_f32_e32 v81, v86, v86
	v_fmac_f32_e32 v82, v88, v88
	v_add_f32_e32 v81, v81, v82
	v_add_f32_e32 v80, v81, v80
	v_mul_f32_e32 v81, v93, v93
	v_mul_f32_e32 v82, v91, v91
	v_fmac_f32_e32 v81, v92, v92
	v_fmac_f32_e32 v82, v90, v90
	v_add_f32_e32 v81, v81, v82
	v_add_f32_e32 v80, v81, v80
	v_mov_b32_e32 v81, v80
	s_nop 1
	v_permlane32_swap_b32_e32 v80, v81
	v_add_f32_e32 v80, v80, v81
	v_mov_b32_e32 v81, v80
	s_nop 1
	v_permlane16_swap_b32_e32 v80, v81
	v_add_f32_e32 v80, v80, v81
	v_fmamk_f32 v80, v80, 0x3c800000, v231
	v_rsq_f32_e32 v80, v80
	s_nop 0
	v_pk_mul_f32 v[94:95], v[94:95], v[80:81] op_sel_hi:[1,0]
	v_pk_mul_f32 v[96:97], v[96:97], v[80:81] op_sel_hi:[1,0]
	v_pk_mul_f32 v[98:99], v[98:99], v[80:81] op_sel_hi:[1,0]
	v_pk_mul_f32 v[100:101], v[100:101], v[80:81] op_sel_hi:[1,0]
	v_pk_mul_f32 v[88:89], v[88:89], v[80:81] op_sel_hi:[1,0]
	v_pk_mul_f32 v[86:87], v[86:87], v[80:81] op_sel_hi:[1,0]
	v_pk_mul_f32 v[90:91], v[90:91], v[80:81] op_sel_hi:[1,0]
	v_pk_mul_f32 v[92:93], v[92:93], v[80:81] op_sel_hi:[1,0]
.LBB0_278:
	v_pk_mul_f32 v[94:95], v[186:187], v[94:95]
	v_pk_mul_f32 v[96:97], v[134:135], v[96:97]
	v_pk_mul_f32 v[98:99], v[188:189], v[98:99]
	s_and_b64 vcc, exec, s[42:43]
	v_pk_mul_f32 v[100:101], v[136:137], v[100:101]
	s_cbranch_vccnz .LBB0_288
	v_mov_b32_e32 v80, v96
	v_mov_b32_e32 v81, v96
	v_mov_b32_e32 v83, v100
	v_mov_b32_e32 v84, v100
	v_mov_b32_e32 v85, v97
	v_mov_b32_e32 v102, v97
	v_mov_b32_e32 v103, v101
	v_mov_b32_e32 v104, v101
	v_mov_b32_e32 v105, v94
	v_mov_b32_e32 v106, v94
	v_mov_b32_e32 v107, v98
	v_mov_b32_e32 v108, v98
	v_mov_b32_e32 v109, v95
	v_mov_b32_e32 v111, v95
	v_mov_b32_e32 v110, v99
	v_mov_b32_e32 v112, v99
	v_permlane16_swap_b32_e32 v80, v81
	v_permlane16_swap_b32_e32 v83, v84
	v_permlane16_swap_b32_e32 v85, v102
	v_permlane16_swap_b32_e32 v103, v104
	v_permlane16_swap_b32_e32 v105, v106
	v_permlane16_swap_b32_e32 v107, v108
	v_permlane16_swap_b32_e32 v109, v111
	v_permlane16_swap_b32_e32 v110, v112
	v_cndmask_b32_e64 v82, v80, v81, s[44:45]
	v_cndmask_b32_e64 v80, v83, v84, s[44:45]
	v_cndmask_b32_e64 v83, v85, v102, s[44:45]
	v_cndmask_b32_e64 v81, v103, v104, s[44:45]
	v_cndmask_b32_e64 v104, v105, v106, s[44:45]
	v_cndmask_b32_e64 v102, v107, v108, s[44:45]
	v_cndmask_b32_e64 v105, v109, v111, s[44:45]
	v_cndmask_b32_e64 v103, v110, v112, s[44:45]
	v_cmp_lt_i32_e32 vcc, 0, v219
	s_and_saveexec_b64 s[2:3], vcc
	s_xor_b64 s[2:3], exec, s[2:3]
	s_cbranch_execz .LBB0_283
	v_cmp_eq_u32_e32 vcc, 1, v219
	s_and_saveexec_b64 s[4:5], vcc
	s_cbranch_execz .LBB0_282
	s_waitcnt vmcnt(2)
	v_pk_mul_f32 v[82:83], v[162:163], v[82:83]
	v_pk_mul_f32 v[84:85], v[164:165], v[104:105]
	v_pk_fma_f32 v[96:97], v[166:167], v[96:97], v[82:83]
	v_pk_mul_f32 v[82:83], v[156:157], v[102:103]
	v_pk_mul_f32 v[80:81], v[154:155], v[80:81]
	v_pk_fma_f32 v[94:95], v[168:169], v[94:95], v[84:85]
	v_pk_fma_f32 v[98:99], v[160:161], v[98:99], v[82:83]
	v_pk_fma_f32 v[100:101], v[158:159], v[100:101], v[80:81]

.LBB0_283:
	s_andn2_saveexec_b64 s[2:3], s[2:3]
	s_cbranch_execz .LBB0_287
	v_cmp_eq_u32_e32 vcc, 0, v219
	s_and_saveexec_b64 s[4:5], vcc
	s_cbranch_execz .LBB0_286
	s_waitcnt vmcnt(2)
	v_pk_mul_f32 v[82:83], v[162:163], v[82:83]
	v_pk_mul_f32 v[84:85], v[164:165], v[104:105]
	v_pk_fma_f32 v[96:97], v[166:167], v[96:97], v[82:83] neg_lo:[0,0,1] neg_hi:[0,0,1]
	v_pk_mul_f32 v[82:83], v[156:157], v[102:103]
	v_pk_mul_f32 v[80:81], v[154:155], v[80:81]
	v_pk_fma_f32 v[94:95], v[168:169], v[94:95], v[84:85] neg_lo:[0,0,1] neg_hi:[0,0,1]
	v_pk_fma_f32 v[98:99], v[160:161], v[98:99], v[82:83] neg_lo:[0,0,1] neg_hi:[0,0,1]
	v_pk_fma_f32 v[100:101], v[158:159], v[100:101], v[80:81] neg_lo:[0,0,1] neg_hi:[0,0,1]

.LBB0_300:
	s_and_b64 vcc, exec, s[42:43]
	s_cbranch_vccnz .Lrope_pf2
	v_add_u32_e32 v64, 0x80, v220
	v_add_u32_e32 v64, s74, v64
	v_ashrrev_i32_e32 v65, 31, v64
	v_readlane_b32 s2, v251, 12
	v_lshlrev_b64 v[66:67], 6, v[64:65]
	v_readlane_b32 s3, v251, 13
	s_nop 1
	v_lshl_add_u64 v[66:67], s[2:3], 0, v[66:67]
	global_load_dwordx4 v[154:157], v[66:67], off offset:48
	global_load_dwordx4 v[162:165], v[66:67], off offset:32
	global_load_dwordx4 v[158:161], v[66:67], off offset:16
	global_load_dwordx4 v[166:169], v[66:67], off
	v_add_u32_e32 v66, 16, v64
	v_ashrrev_i32_e32 v67, 31, v66
	v_lshlrev_b64 v[66:67], 6, v[66:67]
	v_lshl_add_u64 v[66:67], s[2:3], 0, v[66:67]
	global_load_dwordx4 v[138:141], v[66:67], off offset:48
	global_load_dwordx4 v[146:149], v[66:67], off offset:32
	global_load_dwordx4 v[142:145], v[66:67], off offset:16
	global_load_dwordx4 v[150:153], v[66:67], off
.Lrope_pf2:
	v_add_u32_e32 v64, 48, v220
	v_mad_i64_i32 v[64:65], s[2:3], s10, v64, 0
	v_pk_mul_f32 v[68:69], v[132:133], v[72:73]
	v_pk_mul_f32 v[72:73], v[182:183], v[74:75]
	v_pk_mul_f32 v[74:75], v[128:129], v[76:77]
	v_lshl_add_u64 v[76:77], v[64:65], 1, v[184:185]
	v_cvt_pk_bf16_f32 v64, v80, v81
	v_cvt_pk_bf16_f32 v65, v78, v79
	v_cvt_pk_bf16_f32 v66, v84, v85
	v_cvt_pk_bf16_f32 v67, v82, v83
	v_pk_mul_f32 v[70:71], v[130:131], v[70:71]
	global_store_dwordx4 v[76:77], v[64:67], off
	s_and_b64 vcc, exec, s[42:43]
	s_nop 0
	v_cvt_pk_bf16_f32 v64, v70, v71
	v_cvt_pk_bf16_f32 v65, v68, v69
	v_cvt_pk_bf16_f32 v66, v74, v75
	v_cvt_pk_bf16_f32 v67, v72, v73
	global_store_dwordx4 v[76:77], v[64:67], off offset:64
	v_add_u32_e32 v76, 0x80, v220
	s_nop 0
	v_add_u32_e32 v64, s74, v76
	s_cbranch_vccnz .LBB0_302
.LBB0_302:
	v_add_f32_e32 v65, v227, v228
	v_fmamk_f32 v65, v65, 0x3a800000, v231
	v_rsq_f32_e32 v72, v65
	s_and_b64 vcc, exec, s[40:41]
	v_pk_mul_f32 v[62:63], v[62:63], v[72:73] op_sel_hi:[1,0]
	v_pk_mul_f32 v[66:67], v[60:61], v[72:73] op_sel_hi:[1,0]
	v_pk_mul_f32 v[68:69], v[58:59], v[72:73] op_sel_hi:[1,0]
	v_pk_mul_f32 v[70:71], v[56:57], v[72:73] op_sel_hi:[1,0]
	v_pk_mul_f32 v[56:57], v[54:55], v[72:73] op_sel_hi:[1,0]
	v_pk_mul_f32 v[54:55], v[52:53], v[72:73] op_sel_hi:[1,0]
	v_pk_mul_f32 v[58:59], v[50:51], v[72:73] op_sel_hi:[1,0]
	v_pk_mul_f32 v[60:61], v[48:49], v[72:73] op_sel_hi:[1,0]
	s_cbranch_vccnz .LBB0_304
	v_mul_f32_e32 v48, v67, v67
	v_mul_f32_e32 v49, v63, v63
	v_fmac_f32_e32 v48, v66, v66
	v_fmac_f32_e32 v49, v62, v62
	v_add_f32_e32 v48, v48, v49
	v_mul_f32_e32 v49, v71, v71
	v_mul_f32_e32 v50, v69, v69
	v_fmac_f32_e32 v49, v70, v70
	v_fmac_f32_e32 v50, v68, v68
	v_add_f32_e32 v49, v49, v50
	v_add_f32_e32 v48, v48, v49
	v_mul_f32_e32 v49, v55, v55
	v_mul_f32_e32 v50, v57, v57
	v_fmac_f32_e32 v49, v54, v54
	v_fmac_f32_e32 v50, v56, v56
	v_add_f32_e32 v49, v49, v50
	v_add_f32_e32 v48, v49, v48
	v_mul_f32_e32 v49, v61, v61
	v_mul_f32_e32 v50, v59, v59
	v_fmac_f32_e32 v49, v60, v60
	v_fmac_f32_e32 v50, v58, v58
	v_add_f32_e32 v49, v49, v50
	v_add_f32_e32 v48, v49, v48
	v_mov_b32_e32 v49, v48
	s_nop 1
	v_permlane32_swap_b32_e32 v48, v49
	v_add_f32_e32 v48, v48, v49
	v_mov_b32_e32 v49, v48
	s_nop 1
	v_permlane16_swap_b32_e32 v48, v49
	v_add_f32_e32 v48, v48, v49
	v_fmamk_f32 v48, v48, 0x3c800000, v231
	v_rsq_f32_e32 v48, v48
	s_nop 0
	v_pk_mul_f32 v[62:63], v[62:63], v[48:49] op_sel_hi:[1,0]
	v_pk_mul_f32 v[66:67], v[66:67], v[48:49] op_sel_hi:[1,0]
	v_pk_mul_f32 v[68:69], v[68:69], v[48:49] op_sel_hi:[1,0]
	v_pk_mul_f32 v[70:71], v[70:71], v[48:49] op_sel_hi:[1,0]
	v_pk_mul_f32 v[56:57], v[56:57], v[48:49] op_sel_hi:[1,0]
	v_pk_mul_f32 v[54:55], v[54:55], v[48:49] op_sel_hi:[1,0]
	v_pk_mul_f32 v[58:59], v[58:59], v[48:49] op_sel_hi:[1,0]
	v_pk_mul_f32 v[60:61], v[60:61], v[48:49] op_sel_hi:[1,0]
.LBB0_304:
	v_pk_mul_f32 v[62:63], v[186:187], v[62:63]
	v_pk_mul_f32 v[66:67], v[134:135], v[66:67]
	v_pk_mul_f32 v[68:69], v[188:189], v[68:69]
	s_and_b64 vcc, exec, s[42:43]
	v_pk_mul_f32 v[70:71], v[136:137], v[70:71]
	s_cbranch_vccnz .LBB0_314
	v_mov_b32_e32 v48, v66
	v_mov_b32_e32 v49, v66
	v_mov_b32_e32 v51, v70
	v_mov_b32_e32 v52, v70
	v_mov_b32_e32 v53, v67
	v_mov_b32_e32 v65, v67
	v_mov_b32_e32 v72, v71
	v_mov_b32_e32 v73, v71
	v_mov_b32_e32 v74, v62
	v_mov_b32_e32 v75, v62
	v_mov_b32_e32 v77, v68
	v_mov_b32_e32 v78, v68
	v_mov_b32_e32 v79, v63
	v_mov_b32_e32 v81, v63
	v_mov_b32_e32 v80, v69
	v_mov_b32_e32 v82, v69
	v_permlane16_swap_b32_e32 v48, v49
	v_permlane16_swap_b32_e32 v51, v52
	v_permlane16_swap_b32_e32 v53, v65
	v_permlane16_swap_b32_e32 v72, v73
	v_permlane16_swap_b32_e32 v74, v75
	v_permlane16_swap_b32_e32 v77, v78
	v_permlane16_swap_b32_e32 v79, v81
	v_permlane16_swap_b32_e32 v80, v82
	v_cndmask_b32_e64 v50, v48, v49, s[44:45]
	v_cndmask_b32_e64 v48, v51, v52, s[44:45]
	v_cndmask_b32_e64 v51, v53, v65, s[44:45]
	v_cndmask_b32_e64 v49, v72, v73, s[44:45]
	v_cndmask_b32_e64 v74, v74, v75, s[44:45]
	v_cndmask_b32_e64 v72, v77, v78, s[44:45]
	v_cndmask_b32_e64 v75, v79, v81, s[44:45]
	v_cndmask_b32_e64 v73, v80, v82, s[44:45]
	v_cmp_lt_i32_e32 vcc, 0, v219
	s_and_saveexec_b64 s[2:3], vcc
	s_xor_b64 s[2:3], exec, s[2:3]
	s_cbranch_execz .LBB0_309
	v_cmp_eq_u32_e32 vcc, 1, v219
	s_and_saveexec_b64 s[4:5], vcc
	s_cbranch_execz .LBB0_308
	s_waitcnt vmcnt(2)
	v_pk_mul_f32 v[50:51], v[162:163], v[50:51]
	v_pk_mul_f32 v[52:53], v[164:165], v[74:75]
	v_pk_fma_f32 v[66:67], v[166:167], v[66:67], v[50:51]
	v_pk_mul_f32 v[50:51], v[156:157], v[72:73]
	v_pk_mul_f32 v[48:49], v[154:155], v[48:49]
	v_pk_fma_f32 v[62:63], v[168:169], v[62:63], v[52:53]
	v_pk_fma_f32 v[68:69], v[160:161], v[68:69], v[50:51]
	v_pk_fma_f32 v[70:71], v[158:159], v[70:71], v[48:49]

.LBB0_309:
	s_andn2_saveexec_b64 s[2:3], s[2:3]
	s_cbranch_execz .LBB0_313
	v_cmp_eq_u32_e32 vcc, 0, v219
	s_and_saveexec_b64 s[4:5], vcc
	s_cbranch_execz .LBB0_312
	s_waitcnt vmcnt(2)
	v_pk_mul_f32 v[50:51], v[162:163], v[50:51]
	v_pk_mul_f32 v[52:53], v[164:165], v[74:75]
	v_pk_fma_f32 v[66:67], v[166:167], v[66:67], v[50:51] neg_lo:[0,0,1] neg_hi:[0,0,1]
	v_pk_mul_f32 v[50:51], v[156:157], v[72:73]
	v_pk_mul_f32 v[48:49], v[154:155], v[48:49]
	v_pk_fma_f32 v[62:63], v[168:169], v[62:63], v[52:53] neg_lo:[0,0,1] neg_hi:[0,0,1]
	v_pk_fma_f32 v[68:69], v[160:161], v[68:69], v[50:51] neg_lo:[0,0,1] neg_hi:[0,0,1]
	v_pk_fma_f32 v[70:71], v[158:159], v[70:71], v[48:49] neg_lo:[0,0,1] neg_hi:[0,0,1]

.LBB0_326:
	s_and_b64 vcc, exec, s[42:43]
	s_cbranch_vccnz .Lrope_pf3
	v_add_u32_e32 v32, 32, v64
	v_ashrrev_i32_e32 v33, 31, v32
	v_readlane_b32 s2, v251, 12
	v_lshlrev_b64 v[32:33], 6, v[32:33]
	v_readlane_b32 s3, v251, 13
	s_nop 1
	v_lshl_add_u64 v[32:33], s[2:3], 0, v[32:33]
	global_load_dwordx4 v[154:157], v[32:33], off offset:48
	global_load_dwordx4 v[162:165], v[32:33], off offset:32
	global_load_dwordx4 v[158:161], v[32:33], off offset:16
	global_load_dwordx4 v[166:169], v[32:33], off
	v_add_u32_e32 v32, 48, v64
	v_ashrrev_i32_e32 v33, 31, v32
	v_lshlrev_b64 v[32:33], 6, v[32:33]
	v_lshl_add_u64 v[32:33], s[2:3], 0, v[32:33]
	global_load_dwordx4 v[138:141], v[32:33], off offset:48
	global_load_dwordx4 v[146:149], v[32:33], off offset:32
	global_load_dwordx4 v[142:145], v[32:33], off offset:16
	global_load_dwordx4 v[150:153], v[32:33], off
.Lrope_pf3:
	v_add_u32_e32 v32, 0x90, v220
	v_mad_i64_i32 v[32:33], s[2:3], s10, v32, 0
	v_pk_mul_f32 v[36:37], v[132:133], v[40:41]
	v_pk_mul_f32 v[40:41], v[182:183], v[42:43]
	v_pk_mul_f32 v[42:43], v[128:129], v[44:45]
	v_lshl_add_u64 v[44:45], v[32:33], 1, v[184:185]
	v_cvt_pk_bf16_f32 v32, v48, v49
	v_cvt_pk_bf16_f32 v33, v46, v47
	v_cvt_pk_bf16_f32 v34, v52, v53
	v_cvt_pk_bf16_f32 v35, v50, v51
	v_pk_mul_f32 v[38:39], v[130:131], v[38:39]
	global_store_dwordx4 v[44:45], v[32:35], off
	s_and_b64 vcc, exec, s[42:43]
	s_nop 0
	v_cvt_pk_bf16_f32 v32, v38, v39
	v_cvt_pk_bf16_f32 v33, v36, v37
	v_cvt_pk_bf16_f32 v34, v42, v43
	v_cvt_pk_bf16_f32 v35, v40, v41
	global_store_dwordx4 v[44:45], v[32:35], off offset:64
	s_cbranch_vccnz .LBB0_328
.LBB0_328:
	s_nop 0
	v_add_f32_e32 v32, v223, v224
	v_fmamk_f32 v32, v32, 0x3a800000, v231
	v_rsq_f32_e32 v38, v32
	s_and_b64 vcc, exec, s[40:41]
	v_pk_mul_f32 v[30:31], v[30:31], v[38:39] op_sel_hi:[1,0]
	v_pk_mul_f32 v[32:33], v[28:29], v[38:39] op_sel_hi:[1,0]
	v_pk_mul_f32 v[34:35], v[26:27], v[38:39] op_sel_hi:[1,0]
	v_pk_mul_f32 v[36:37], v[24:25], v[38:39] op_sel_hi:[1,0]
	v_pk_mul_f32 v[24:25], v[22:23], v[38:39] op_sel_hi:[1,0]
	v_pk_mul_f32 v[22:23], v[20:21], v[38:39] op_sel_hi:[1,0]
	v_pk_mul_f32 v[26:27], v[18:19], v[38:39] op_sel_hi:[1,0]
	v_pk_mul_f32 v[28:29], v[16:17], v[38:39] op_sel_hi:[1,0]
	s_cbranch_vccnz .LBB0_330
	v_mul_f32_e32 v16, v33, v33
	v_mul_f32_e32 v17, v31, v31
	v_fmac_f32_e32 v16, v32, v32
	v_fmac_f32_e32 v17, v30, v30
	v_add_f32_e32 v16, v16, v17
	v_mul_f32_e32 v17, v37, v37
	v_mul_f32_e32 v18, v35, v35
	v_fmac_f32_e32 v17, v36, v36
	v_fmac_f32_e32 v18, v34, v34
	v_add_f32_e32 v17, v17, v18
	v_add_f32_e32 v16, v16, v17
	v_mul_f32_e32 v17, v23, v23
	v_mul_f32_e32 v18, v25, v25
	v_fmac_f32_e32 v17, v22, v22
	v_fmac_f32_e32 v18, v24, v24
	v_add_f32_e32 v17, v17, v18
	v_add_f32_e32 v16, v17, v16
	v_mul_f32_e32 v17, v29, v29
	v_mul_f32_e32 v18, v27, v27
	v_fmac_f32_e32 v17, v28, v28
	v_fmac_f32_e32 v18, v26, v26
	v_add_f32_e32 v17, v17, v18
	v_add_f32_e32 v16, v17, v16
	v_mov_b32_e32 v17, v16
	s_nop 1
	v_permlane32_swap_b32_e32 v16, v17
	v_add_f32_e32 v16, v16, v17
	v_mov_b32_e32 v17, v16
	s_nop 1
	v_permlane16_swap_b32_e32 v16, v17
	v_add_f32_e32 v16, v16, v17
	v_fmamk_f32 v16, v16, 0x3c800000, v231
	v_rsq_f32_e32 v16, v16
	s_nop 0
	v_pk_mul_f32 v[30:31], v[30:31], v[16:17] op_sel_hi:[1,0]
	v_pk_mul_f32 v[32:33], v[32:33], v[16:17] op_sel_hi:[1,0]
	v_pk_mul_f32 v[34:35], v[34:35], v[16:17] op_sel_hi:[1,0]
	v_pk_mul_f32 v[36:37], v[36:37], v[16:17] op_sel_hi:[1,0]
	v_pk_mul_f32 v[24:25], v[24:25], v[16:17] op_sel_hi:[1,0]
	v_pk_mul_f32 v[22:23], v[22:23], v[16:17] op_sel_hi:[1,0]
	v_pk_mul_f32 v[26:27], v[26:27], v[16:17] op_sel_hi:[1,0]
	v_pk_mul_f32 v[28:29], v[28:29], v[16:17] op_sel_hi:[1,0]
.LBB0_330:
	v_pk_mul_f32 v[30:31], v[186:187], v[30:31]
	v_pk_mul_f32 v[32:33], v[134:135], v[32:33]
	v_pk_mul_f32 v[34:35], v[188:189], v[34:35]
	s_and_b64 vcc, exec, s[42:43]
	v_pk_mul_f32 v[36:37], v[136:137], v[36:37]
	s_cbranch_vccnz .LBB0_340
	v_mov_b32_e32 v16, v32
	v_mov_b32_e32 v17, v32
	v_mov_b32_e32 v19, v36
	v_mov_b32_e32 v20, v36
	v_mov_b32_e32 v21, v33
	v_mov_b32_e32 v38, v33
	v_mov_b32_e32 v39, v37
	v_mov_b32_e32 v40, v37
	v_mov_b32_e32 v41, v30
	v_mov_b32_e32 v42, v30
	v_mov_b32_e32 v43, v34
	v_mov_b32_e32 v44, v34
	v_mov_b32_e32 v45, v31
	v_mov_b32_e32 v47, v31
	v_mov_b32_e32 v46, v35
	v_mov_b32_e32 v48, v35
	v_permlane16_swap_b32_e32 v16, v17
	v_permlane16_swap_b32_e32 v19, v20
	v_permlane16_swap_b32_e32 v21, v38
	v_permlane16_swap_b32_e32 v39, v40
	v_permlane16_swap_b32_e32 v41, v42
	v_permlane16_swap_b32_e32 v43, v44
	v_permlane16_swap_b32_e32 v45, v47
	v_permlane16_swap_b32_e32 v46, v48
	v_cndmask_b32_e64 v18, v16, v17, s[44:45]
	v_cndmask_b32_e64 v16, v19, v20, s[44:45]
	v_cndmask_b32_e64 v19, v21, v38, s[44:45]
	v_cndmask_b32_e64 v17, v39, v40, s[44:45]
	v_cndmask_b32_e64 v40, v41, v42, s[44:45]
	v_cndmask_b32_e64 v38, v43, v44, s[44:45]
	v_cndmask_b32_e64 v41, v45, v47, s[44:45]
	v_cndmask_b32_e64 v39, v46, v48, s[44:45]
	v_cmp_lt_i32_e32 vcc, 0, v219
	s_and_saveexec_b64 s[2:3], vcc
	s_xor_b64 s[2:3], exec, s[2:3]
	s_cbranch_execz .LBB0_335
	v_cmp_eq_u32_e32 vcc, 1, v219
	s_and_saveexec_b64 s[4:5], vcc
	s_cbranch_execz .LBB0_334
	s_waitcnt vmcnt(2)
	v_pk_mul_f32 v[18:19], v[162:163], v[18:19]
	v_pk_mul_f32 v[20:21], v[164:165], v[40:41]
	v_pk_fma_f32 v[32:33], v[166:167], v[32:33], v[18:19]
	v_pk_mul_f32 v[18:19], v[156:157], v[38:39]
	v_pk_mul_f32 v[16:17], v[154:155], v[16:17]
	v_pk_fma_f32 v[30:31], v[168:169], v[30:31], v[20:21]
	v_pk_fma_f32 v[34:35], v[160:161], v[34:35], v[18:19]
	v_pk_fma_f32 v[36:37], v[158:159], v[36:37], v[16:17]

.LBB0_335:
	s_andn2_saveexec_b64 s[2:3], s[2:3]
	s_cbranch_execz .LBB0_339
	v_cmp_eq_u32_e32 vcc, 0, v219
	s_and_saveexec_b64 s[4:5], vcc
	s_cbranch_execz .LBB0_338
	s_waitcnt vmcnt(2)
	v_pk_mul_f32 v[18:19], v[162:163], v[18:19]
	v_pk_mul_f32 v[20:21], v[164:165], v[40:41]
	v_pk_fma_f32 v[32:33], v[166:167], v[32:33], v[18:19] neg_lo:[0,0,1] neg_hi:[0,0,1]
	v_pk_mul_f32 v[18:19], v[156:157], v[38:39]
	v_pk_mul_f32 v[16:17], v[154:155], v[16:17]
	v_pk_fma_f32 v[30:31], v[168:169], v[30:31], v[20:21] neg_lo:[0,0,1] neg_hi:[0,0,1]
	v_pk_fma_f32 v[34:35], v[160:161], v[34:35], v[18:19] neg_lo:[0,0,1] neg_hi:[0,0,1]
	v_pk_fma_f32 v[36:37], v[158:159], v[36:37], v[16:17] neg_lo:[0,0,1] neg_hi:[0,0,1]
